# P3 epilogue: the four column waves of a row half add their row sums of squares through LDS, one 32-lane rss atomic per wave and tile instead of two 64-lane ones
# speedup vs baseline: 1.0038x; 1.0028x over previous
;     __device__ __forceinline__ void operator()(f32x4 (&acc)[2][2][4][2], const Unit& u, int wr, int wc, int fr, int fq) const {
;         asm volatile("" : "+v"(fr), "+v"(fq));
;         const int col0 = u.pn * 256 + wc * 32 + 8 * fq;
;     ...
; #pragma unroll
;         for (int ai = 0; ai < 2; ++ai) {
;             RES1_LD(0) RES1_LD(1) RES1_LD(2) RES1_LD(3)
;             RES1_DO(0) RES1_DO(1) RES1_DO(2) RES1_DO(3)
;             asm volatile("" ::: "memory");
;         }
.LBB0_472:
	s_lshl_b32 s0, s0, 8
	s_add_i32 s0, s0, s41
	s_lshl_b32 s1, s2, 8
	s_or_b32 s1, s1, s42
	s_cmp_lt_i32 s0, s40
	s_cselect_b32 s26, s36, s38
	s_cselect_b32 s27, s37, s39
	s_cselect_b32 s2, 0, s40
	s_sub_i32 s2, s0, s2
	s_lshl_b32 s2, s2, 12
	s_lshl_b32 s15, s1, 2
	s_add_i32 s2, s2, s15
	s_add_u32 s26, s26, s2
	s_addc_u32 s27, s27, 0
	v_lshlrev_b32_e32 v228, 12, v204
	v_lshl_or_b32 v228, v205, 5, v228
	s_lshl_b32 s2, s0, 11
	s_lshl_b32 s15, s1, 1
	s_add_i32 s2, s2, s15
	s_add_u32 s28, s62, s2
	s_addc_u32 s29, s63, 0
	s_lshl_b32 s2, s0, 2
	s_add_u32 s6, s60, s2
	s_addc_u32 s7, s61, 0
	global_load_dwordx4 v[128:131], v228, s[26:27]
	global_load_dwordx4 v[132:135], v228, s[26:27] offset:16
	global_load_dwordx4 v[136:139], v228, s[26:27] offset:512
	global_load_dwordx4 v[140:143], v228, s[26:27] offset:528
	s_add_u32 s26, s26, 0x10000
	s_addc_u32 s27, s27, 0
	global_load_dwordx4 v[144:147], v228, s[26:27]
	global_load_dwordx4 v[148:151], v228, s[26:27] offset:16
	global_load_dwordx4 v[152:155], v228, s[26:27] offset:512
	global_load_dwordx4 v[156:159], v228, s[26:27] offset:528
	s_add_u32 s26, s26, 0x10000
	s_addc_u32 s27, s27, 0
	global_load_dwordx4 v[160:163], v228, s[26:27]
	global_load_dwordx4 v[164:167], v228, s[26:27] offset:16
	global_load_dwordx4 v[168:171], v228, s[26:27] offset:512
	global_load_dwordx4 v[172:175], v228, s[26:27] offset:528
	s_add_u32 s26, s26, 0x10000
	s_addc_u32 s27, s27, 0
	global_load_dwordx4 v[212:215], v228, s[26:27]
	global_load_dwordx4 v[216:219], v228, s[26:27] offset:16
	global_load_dwordx4 v[220:223], v228, s[26:27] offset:512
	global_load_dwordx4 v[224:227], v228, s[26:27] offset:528
	s_add_u32 s26, s26, 0x50000
	s_addc_u32 s27, s27, 0
	global_load_dwordx4 v[232:235], v228, s[26:27]
	global_load_dwordx4 v[236:239], v228, s[26:27] offset:16
	global_load_dwordx4 v[240:243], v228, s[26:27] offset:512
	global_load_dwordx4 v[244:247], v228, s[26:27] offset:528
	v_lshlrev_b32_e32 v229, 11, v204
	v_lshl_or_b32 v229, v205, 4, v229
	v_lshlrev_b32_e32 v230, 2, v210
	s_lshl_b32 s15, s41, 5
	s_lshl_b32 s17, s42, 3
	s_add_i32 s15, s15, s17
	s_add_i32 s15, s15, 0x20000
	v_add_u32_e32 v250, s15, v230
	v_xor_b32_e32 v231, 64, v230
	v_xor_b32_e32 v252, 0x80, v230
	v_and_b32_e32 v253, 1, v205
	v_cmp_ne_u32_e64 s[50:51], 0, v253
	v_and_b32_e32 v253, 2, v205
	v_cmp_ne_u32_e64 s[52:53], 0, v253
	s_waitcnt vmcnt(16)
	v_pk_add_f32 v[124:125], v[124:125], v[128:129]
	v_pk_add_f32 v[126:127], v[126:127], v[130:131]
	v_pk_add_f32 v[120:121], v[120:121], v[132:133]
	v_pk_add_f32 v[122:123], v[122:123], v[134:135]
	v_pk_add_f32 v[116:117], v[116:117], v[136:137]
	v_pk_add_f32 v[118:119], v[118:119], v[138:139]
	v_pk_add_f32 v[112:113], v[112:113], v[140:141]
	v_pk_add_f32 v[114:115], v[114:115], v[142:143]
	v_pk_mul_f32 v[128:129], v[124:125], v[124:125]
	v_pk_mul_f32 v[130:131], v[126:127], v[126:127]
	v_pk_fma_f32 v[128:129], v[120:121], v[120:121], v[128:129]
	v_pk_fma_f32 v[130:131], v[122:123], v[122:123], v[130:131]
	v_pk_fma_f32 v[128:129], v[116:117], v[116:117], v[128:129]
	v_pk_fma_f32 v[130:131], v[118:119], v[118:119], v[130:131]
	v_pk_fma_f32 v[128:129], v[112:113], v[112:113], v[128:129]
	v_pk_fma_f32 v[130:131], v[114:115], v[114:115], v[130:131]
	v_cvt_pk_bf16_f32 v132, v124, v125
	v_cvt_pk_bf16_f32 v133, v126, v127
	v_cvt_pk_bf16_f32 v134, v120, v121
	v_cvt_pk_bf16_f32 v135, v122, v123
	v_add_f32_e32 v128, v128, v129
	v_cvt_pk_bf16_f32 v136, v116, v117
	v_cvt_pk_bf16_f32 v137, v118, v119
	v_add_f32_e32 v130, v130, v131
	v_cvt_pk_bf16_f32 v138, v112, v113
	v_cvt_pk_bf16_f32 v139, v114, v115
	v_add_f32_e32 v192, v128, v130
	global_store_dwordx4 v229, v[132:135], s[28:29]
	global_store_dwordx4 v229, v[136:139], s[28:29] offset:256
	s_add_u32 s26, s26, 0x10000
	s_addc_u32 s27, s27, 0
	global_load_dwordx4 v[128:131], v228, s[26:27]
	global_load_dwordx4 v[132:135], v228, s[26:27] offset:16
	global_load_dwordx4 v[136:139], v228, s[26:27] offset:512
	global_load_dwordx4 v[140:143], v228, s[26:27] offset:528
	s_waitcnt vmcnt(18)
	v_pk_add_f32 v[108:109], v[108:109], v[144:145]
	v_pk_add_f32 v[110:111], v[110:111], v[146:147]
	v_pk_add_f32 v[104:105], v[104:105], v[148:149]
	v_pk_add_f32 v[106:107], v[106:107], v[150:151]
	v_pk_add_f32 v[100:101], v[100:101], v[152:153]
	v_pk_add_f32 v[102:103], v[102:103], v[154:155]
	v_pk_add_f32 v[96:97], v[96:97], v[156:157]
	v_pk_add_f32 v[98:99], v[98:99], v[158:159]
	v_pk_mul_f32 v[144:145], v[108:109], v[108:109]
	v_pk_mul_f32 v[146:147], v[110:111], v[110:111]
	v_pk_fma_f32 v[144:145], v[104:105], v[104:105], v[144:145]
	v_pk_fma_f32 v[146:147], v[106:107], v[106:107], v[146:147]
	v_pk_fma_f32 v[144:145], v[100:101], v[100:101], v[144:145]
	v_pk_fma_f32 v[146:147], v[102:103], v[102:103], v[146:147]
	v_pk_fma_f32 v[144:145], v[96:97], v[96:97], v[144:145]
	v_pk_fma_f32 v[146:147], v[98:99], v[98:99], v[146:147]
	v_cvt_pk_bf16_f32 v148, v108, v109
	v_cvt_pk_bf16_f32 v149, v110, v111
	v_cvt_pk_bf16_f32 v150, v104, v105
	v_cvt_pk_bf16_f32 v151, v106, v107
	v_add_f32_e32 v144, v144, v145
	v_cvt_pk_bf16_f32 v152, v100, v101
	v_cvt_pk_bf16_f32 v153, v102, v103
	v_add_f32_e32 v146, v146, v147
	v_cvt_pk_bf16_f32 v154, v96, v97
	v_cvt_pk_bf16_f32 v155, v98, v99
	v_add_f32_e32 v193, v144, v146
	s_add_u32 s28, s28, 0x8000
	s_addc_u32 s29, s29, 0
	global_store_dwordx4 v229, v[148:151], s[28:29]
	global_store_dwordx4 v229, v[152:155], s[28:29] offset:256
	s_add_u32 s26, s26, 0x10000
	s_addc_u32 s27, s27, 0
	global_load_dwordx4 v[144:147], v228, s[26:27]
	global_load_dwordx4 v[148:151], v228, s[26:27] offset:16
	global_load_dwordx4 v[152:155], v228, s[26:27] offset:512
	global_load_dwordx4 v[156:159], v228, s[26:27] offset:528
	s_waitcnt vmcnt(20)
	v_pk_add_f32 v[92:93], v[92:93], v[160:161]
	v_pk_add_f32 v[94:95], v[94:95], v[162:163]
	v_pk_add_f32 v[88:89], v[88:89], v[164:165]
	v_pk_add_f32 v[90:91], v[90:91], v[166:167]
	v_pk_add_f32 v[84:85], v[84:85], v[168:169]
	v_pk_add_f32 v[86:87], v[86:87], v[170:171]
	v_pk_add_f32 v[80:81], v[80:81], v[172:173]
	v_pk_add_f32 v[82:83], v[82:83], v[174:175]
	v_pk_mul_f32 v[160:161], v[92:93], v[92:93]
	v_pk_mul_f32 v[162:163], v[94:95], v[94:95]
	v_pk_fma_f32 v[160:161], v[88:89], v[88:89], v[160:161]
	v_pk_fma_f32 v[162:163], v[90:91], v[90:91], v[162:163]
	v_pk_fma_f32 v[160:161], v[84:85], v[84:85], v[160:161]
	v_pk_fma_f32 v[162:163], v[86:87], v[86:87], v[162:163]
	v_pk_fma_f32 v[160:161], v[80:81], v[80:81], v[160:161]
	v_pk_fma_f32 v[162:163], v[82:83], v[82:83], v[162:163]
	v_cvt_pk_bf16_f32 v164, v92, v93
	v_cvt_pk_bf16_f32 v165, v94, v95
	v_cvt_pk_bf16_f32 v166, v88, v89
	v_cvt_pk_bf16_f32 v167, v90, v91
	v_add_f32_e32 v160, v160, v161
	v_cvt_pk_bf16_f32 v168, v84, v85
	v_cvt_pk_bf16_f32 v169, v86, v87
	v_add_f32_e32 v162, v162, v163
	v_cvt_pk_bf16_f32 v170, v80, v81
	v_cvt_pk_bf16_f32 v171, v82, v83
	v_add_f32_e32 v194, v160, v162
	s_add_u32 s28, s28, 0x8000
	s_addc_u32 s29, s29, 0
	global_store_dwordx4 v229, v[164:167], s[28:29]
	global_store_dwordx4 v229, v[168:171], s[28:29] offset:256
	s_add_u32 s26, s26, 0x10000
	s_addc_u32 s27, s27, 0
	global_load_dwordx4 v[160:163], v228, s[26:27]
	global_load_dwordx4 v[164:167], v228, s[26:27] offset:16
	global_load_dwordx4 v[168:171], v228, s[26:27] offset:512
	global_load_dwordx4 v[172:175], v228, s[26:27] offset:528
	s_waitcnt vmcnt(22)
	v_pk_add_f32 v[76:77], v[76:77], v[212:213]
	v_pk_add_f32 v[78:79], v[78:79], v[214:215]
	v_pk_add_f32 v[72:73], v[72:73], v[216:217]
	v_pk_add_f32 v[74:75], v[74:75], v[218:219]
	v_pk_add_f32 v[68:69], v[68:69], v[220:221]
	v_pk_add_f32 v[70:71], v[70:71], v[222:223]
	v_pk_add_f32 v[64:65], v[64:65], v[224:225]
	v_pk_add_f32 v[66:67], v[66:67], v[226:227]
	v_pk_mul_f32 v[212:213], v[76:77], v[76:77]
	v_pk_mul_f32 v[214:215], v[78:79], v[78:79]
	v_pk_fma_f32 v[212:213], v[72:73], v[72:73], v[212:213]
	v_pk_fma_f32 v[214:215], v[74:75], v[74:75], v[214:215]
	v_pk_fma_f32 v[212:213], v[68:69], v[68:69], v[212:213]
	v_pk_fma_f32 v[214:215], v[70:71], v[70:71], v[214:215]
	v_pk_fma_f32 v[212:213], v[64:65], v[64:65], v[212:213]
	v_pk_fma_f32 v[214:215], v[66:67], v[66:67], v[214:215]
	v_cvt_pk_bf16_f32 v216, v76, v77
	v_cvt_pk_bf16_f32 v217, v78, v79
	v_cvt_pk_bf16_f32 v218, v72, v73
	v_cvt_pk_bf16_f32 v219, v74, v75
	v_add_f32_e32 v212, v212, v213
	v_cvt_pk_bf16_f32 v220, v68, v69
	v_cvt_pk_bf16_f32 v221, v70, v71
	v_add_f32_e32 v214, v214, v215
	v_cvt_pk_bf16_f32 v222, v64, v65
	v_cvt_pk_bf16_f32 v223, v66, v67
	v_add_f32_e32 v195, v212, v214
	s_add_u32 s28, s28, 0x8000
	s_addc_u32 s29, s29, 0
	global_store_dwordx4 v229, v[216:219], s[28:29]
	global_store_dwordx4 v229, v[220:223], s[28:29] offset:256
	v_cndmask_b32_e64 v196, v192, v193, s[50:51]
	v_cndmask_b32_e64 v197, v193, v192, s[50:51]
	v_cndmask_b32_e64 v198, v194, v195, s[50:51]
	v_cndmask_b32_e64 v199, v195, v194, s[50:51]
	ds_bpermute_b32 v200, v231, v197
	ds_bpermute_b32 v201, v231, v199
	s_waitcnt lgkmcnt(0)
	v_add_f32_e32 v196, v196, v200
	v_add_f32_e32 v198, v198, v201
	v_cndmask_b32_e64 v202, v196, v198, s[52:53]
	v_cndmask_b32_e64 v203, v198, v196, s[52:53]
	ds_bpermute_b32 v248, v252, v203
	s_waitcnt lgkmcnt(0)
	v_add_f32_e32 v249, v202, v248
	ds_write_b32 v250, v249
	s_waitcnt vmcnt(20)
	v_pk_add_f32 v[60:61], v[60:61], v[232:233]
	v_pk_add_f32 v[62:63], v[62:63], v[234:235]
	v_pk_add_f32 v[56:57], v[56:57], v[236:237]
	v_pk_add_f32 v[58:59], v[58:59], v[238:239]
	v_pk_add_f32 v[52:53], v[52:53], v[240:241]
	v_pk_add_f32 v[54:55], v[54:55], v[242:243]
	v_pk_add_f32 v[48:49], v[48:49], v[244:245]
	v_pk_add_f32 v[50:51], v[50:51], v[246:247]
	v_pk_mul_f32 v[232:233], v[60:61], v[60:61]
	v_pk_mul_f32 v[234:235], v[62:63], v[62:63]
	v_pk_fma_f32 v[232:233], v[56:57], v[56:57], v[232:233]
	v_pk_fma_f32 v[234:235], v[58:59], v[58:59], v[234:235]
	v_pk_fma_f32 v[232:233], v[52:53], v[52:53], v[232:233]
	v_pk_fma_f32 v[234:235], v[54:55], v[54:55], v[234:235]
	v_pk_fma_f32 v[232:233], v[48:49], v[48:49], v[232:233]
	v_pk_fma_f32 v[234:235], v[50:51], v[50:51], v[234:235]
	v_cvt_pk_bf16_f32 v236, v60, v61
	v_cvt_pk_bf16_f32 v237, v62, v63
	v_cvt_pk_bf16_f32 v238, v56, v57
	v_cvt_pk_bf16_f32 v239, v58, v59
	v_add_f32_e32 v232, v232, v233
	v_cvt_pk_bf16_f32 v240, v52, v53
	v_cvt_pk_bf16_f32 v241, v54, v55
	v_add_f32_e32 v234, v234, v235
	v_cvt_pk_bf16_f32 v242, v48, v49
	v_cvt_pk_bf16_f32 v243, v50, v51
	v_add_f32_e32 v192, v232, v234
	s_add_u32 s28, s28, 0x28000
	s_addc_u32 s29, s29, 0
	global_store_dwordx4 v229, v[236:239], s[28:29]
	global_store_dwordx4 v229, v[240:243], s[28:29] offset:256
	s_waitcnt vmcnt(16)
;     __device__ __forceinline__ void operator()(f32x4 (&acc)[2][2][4][2], const Unit& u, int wr, int wc, int fr, int fq) const {
;     ...
; #pragma unroll
;         for (int ai = 0; ai < 2; ++ai) {
;             RES1_LD(0) RES1_LD(1) RES1_LD(2) RES1_LD(3)
;             RES1_DO(0) RES1_DO(1) RES1_DO(2) RES1_DO(3)
;             asm volatile("" ::: "memory");
;         }
	v_pk_add_f32 v[44:45], v[44:45], v[128:129]
	v_pk_add_f32 v[46:47], v[46:47], v[130:131]
	v_pk_add_f32 v[40:41], v[40:41], v[132:133]
	v_pk_add_f32 v[42:43], v[42:43], v[134:135]
	v_pk_add_f32 v[36:37], v[36:37], v[136:137]
	v_pk_add_f32 v[38:39], v[38:39], v[138:139]
	v_pk_add_f32 v[32:33], v[32:33], v[140:141]
	v_pk_add_f32 v[34:35], v[34:35], v[142:143]
	v_pk_mul_f32 v[128:129], v[44:45], v[44:45]
	v_pk_mul_f32 v[130:131], v[46:47], v[46:47]
	v_pk_fma_f32 v[128:129], v[40:41], v[40:41], v[128:129]
	v_pk_fma_f32 v[130:131], v[42:43], v[42:43], v[130:131]
	v_pk_fma_f32 v[128:129], v[36:37], v[36:37], v[128:129]
	v_pk_fma_f32 v[130:131], v[38:39], v[38:39], v[130:131]
	v_pk_fma_f32 v[128:129], v[32:33], v[32:33], v[128:129]
	v_pk_fma_f32 v[130:131], v[34:35], v[34:35], v[130:131]
	v_cvt_pk_bf16_f32 v132, v44, v45
	v_cvt_pk_bf16_f32 v133, v46, v47
	v_cvt_pk_bf16_f32 v134, v40, v41
	v_cvt_pk_bf16_f32 v135, v42, v43
	v_add_f32_e32 v128, v128, v129
	v_cvt_pk_bf16_f32 v136, v36, v37
	v_cvt_pk_bf16_f32 v137, v38, v39
	v_add_f32_e32 v130, v130, v131
	v_cvt_pk_bf16_f32 v138, v32, v33
	v_cvt_pk_bf16_f32 v139, v34, v35
	v_add_f32_e32 v193, v128, v130
	s_add_u32 s28, s28, 0x8000
	s_addc_u32 s29, s29, 0
	global_store_dwordx4 v229, v[132:135], s[28:29]
	global_store_dwordx4 v229, v[136:139], s[28:29] offset:256
	s_waitcnt vmcnt(12)
	v_pk_add_f32 v[28:29], v[28:29], v[144:145]
	v_pk_add_f32 v[30:31], v[30:31], v[146:147]
	v_pk_add_f32 v[24:25], v[24:25], v[148:149]
	v_pk_add_f32 v[26:27], v[26:27], v[150:151]
	v_pk_add_f32 v[20:21], v[20:21], v[152:153]
	v_pk_add_f32 v[22:23], v[22:23], v[154:155]
	v_pk_add_f32 v[16:17], v[16:17], v[156:157]
	v_pk_add_f32 v[18:19], v[18:19], v[158:159]
	v_pk_mul_f32 v[144:145], v[28:29], v[28:29]
	v_pk_mul_f32 v[146:147], v[30:31], v[30:31]
	v_pk_fma_f32 v[144:145], v[24:25], v[24:25], v[144:145]
	v_pk_fma_f32 v[146:147], v[26:27], v[26:27], v[146:147]
	v_pk_fma_f32 v[144:145], v[20:21], v[20:21], v[144:145]
	v_pk_fma_f32 v[146:147], v[22:23], v[22:23], v[146:147]
	v_pk_fma_f32 v[144:145], v[16:17], v[16:17], v[144:145]
	v_pk_fma_f32 v[146:147], v[18:19], v[18:19], v[146:147]
	v_cvt_pk_bf16_f32 v148, v28, v29
	v_cvt_pk_bf16_f32 v149, v30, v31
	v_cvt_pk_bf16_f32 v150, v24, v25
	v_cvt_pk_bf16_f32 v151, v26, v27
	v_add_f32_e32 v144, v144, v145
	v_cvt_pk_bf16_f32 v152, v20, v21
	v_cvt_pk_bf16_f32 v153, v22, v23
	v_add_f32_e32 v146, v146, v147
	v_cvt_pk_bf16_f32 v154, v16, v17
	v_cvt_pk_bf16_f32 v155, v18, v19
	v_add_f32_e32 v194, v144, v146
	s_add_u32 s28, s28, 0x8000
	s_addc_u32 s29, s29, 0
	global_store_dwordx4 v229, v[148:151], s[28:29]
	global_store_dwordx4 v229, v[152:155], s[28:29] offset:256
	s_waitcnt vmcnt(8)
	v_pk_add_f32 v[12:13], v[12:13], v[160:161]
	v_pk_add_f32 v[14:15], v[14:15], v[162:163]
	v_pk_add_f32 v[8:9], v[8:9], v[164:165]
	v_pk_add_f32 v[10:11], v[10:11], v[166:167]
	v_pk_add_f32 v[4:5], v[4:5], v[168:169]
	v_pk_add_f32 v[6:7], v[6:7], v[170:171]
	v_pk_add_f32 v[0:1], v[0:1], v[172:173]
	v_pk_add_f32 v[2:3], v[2:3], v[174:175]
	v_pk_mul_f32 v[160:161], v[12:13], v[12:13]
	v_pk_mul_f32 v[162:163], v[14:15], v[14:15]
	v_pk_fma_f32 v[160:161], v[8:9], v[8:9], v[160:161]
	v_pk_fma_f32 v[162:163], v[10:11], v[10:11], v[162:163]
	v_pk_fma_f32 v[160:161], v[4:5], v[4:5], v[160:161]
	v_pk_fma_f32 v[162:163], v[6:7], v[6:7], v[162:163]
	v_pk_fma_f32 v[160:161], v[0:1], v[0:1], v[160:161]
	v_pk_fma_f32 v[162:163], v[2:3], v[2:3], v[162:163]
	v_cvt_pk_bf16_f32 v164, v12, v13
	v_cvt_pk_bf16_f32 v165, v14, v15
	v_cvt_pk_bf16_f32 v166, v8, v9
	v_cvt_pk_bf16_f32 v167, v10, v11
	v_add_f32_e32 v160, v160, v161
	v_cvt_pk_bf16_f32 v168, v4, v5
	v_cvt_pk_bf16_f32 v169, v6, v7
	v_add_f32_e32 v162, v162, v163
	v_cvt_pk_bf16_f32 v170, v0, v1
	v_cvt_pk_bf16_f32 v171, v2, v3
	v_add_f32_e32 v195, v160, v162
	s_add_u32 s28, s28, 0x8000
	s_addc_u32 s29, s29, 0
	global_store_dwordx4 v229, v[164:167], s[28:29]
	global_store_dwordx4 v229, v[168:171], s[28:29] offset:256
	v_cndmask_b32_e64 v196, v192, v193, s[50:51]
	v_cndmask_b32_e64 v197, v193, v192, s[50:51]
	v_cndmask_b32_e64 v198, v194, v195, s[50:51]
	v_cndmask_b32_e64 v199, v195, v194, s[50:51]
	ds_bpermute_b32 v200, v231, v197
	ds_bpermute_b32 v201, v231, v199
	s_waitcnt lgkmcnt(0)
	v_add_f32_e32 v196, v196, v200
	v_add_f32_e32 v198, v198, v201
	v_cndmask_b32_e64 v202, v196, v198, s[52:53]
	v_cndmask_b32_e64 v203, v198, v196, s[52:53]
	ds_bpermute_b32 v248, v252, v203
	s_waitcnt lgkmcnt(0)
	v_add_f32_e32 v249, v202, v248
	ds_write_b32 v250, v249 offset:1024
	s_waitcnt lgkmcnt(0)
	s_barrier
	s_lshr_b32 s15, s42, 6
	s_bfe_u32 s17, s42, 0x10005
	s_lshl_b32 s0, s41, 5
	s_lshl_b32 s1, s15, 10
	s_add_i32 s0, s0, s1
	s_lshl_b32 s1, s17, 7
	s_add_i32 s0, s0, s1
	s_add_i32 s0, s0, 0x20000
	v_add_u32_e32 v250, s0, v230
	ds_read_b32 v196, v250
	ds_read_b32 v197, v250 offset:256
	ds_read_b32 v198, v250 offset:512
	ds_read_b32 v199, v250 offset:768
	s_lshl_b32 s0, s15, 9
	s_add_i32 s0, s0, s1
	v_add_u32_e32 v251, s0, v230
	s_waitcnt lgkmcnt(0)
	v_add_f32_e32 v196, v196, v197
	v_add_f32_e32 v196, v196, v198
	v_add_f32_e32 v196, v196, v199
	s_mov_b32 exec_hi, 0
	s_nop 1
	global_atomic_add_f32 v251, v196, s[6:7]
	s_mov_b32 exec_hi, -1
	s_andn2_b64 vcc, exec, s[4:5]
	s_mov_b64 s[0:1], -1
	s_cbranch_vccnz .LBB0_461
	s_andn2_b64 vcc, exec, s[8:9]
	s_cbranch_vccnz .LBB0_460
	s_barrier
	s_branch .LBB0_460
